# attention fast trip in two per-half copies: priority raised in front of the early step barrier and dropped to the half's base level behind the tail
# baseline (speedup 1.0000x reference)
.Lfast3:
	v_readfirstlane_b32 s5, v234
	s_nop 3
	s_bfe_u32 s5, s5, 0x10008
	s_cmp_lg_u32 s5, 0
	s_cbranch_scc1 .Lfast3l_head

.Lf3e_0_486:
	s_waitcnt lgkmcnt(14)
	v_mfma_f32_32x32x16_bf16 v[18:33], v[138:141], v[178:181], v[18:33]
	v_exp_f32_e32 v98, v98
	v_exp_f32_e32 v99, v99
	v_exp_f32_e32 v100, v100
	v_exp_f32_e32 v101, v101
	ds_read_b128 v[62:65], v202 offset:16384
	ds_read_b128 v[178:181], v202 offset:18432
	s_waitcnt lgkmcnt(14)
	v_mfma_f32_32x32x16_bf16 v[2:17], v[138:141], v[174:177], v[2:17]
	v_exp_f32_e32 v102, v102
	v_exp_f32_e32 v103, v103
	v_exp_f32_e32 v104, v104
	v_exp_f32_e32 v105, v105
	ds_read_b128 v[174:177], v202 offset:16896
	ds_read_b128 v[170:173], v202 offset:18944
	s_waitcnt lgkmcnt(14)
	v_mfma_f32_32x32x16_bf16 v[18:33], v[130:133], v[66:69], v[18:33]
	v_exp_f32_e32 v106, v106
	v_exp_f32_e32 v107, v107
	v_exp_f32_e32 v108, v108
	v_exp_f32_e32 v109, v109
	ds_read_b128 v[166:169], v202 offset:20480
	ds_read_b128 v[162:165], v202 offset:20992
	s_waitcnt lgkmcnt(14)
	v_mfma_f32_32x32x16_bf16 v[2:17], v[130:133], v[70:73], v[2:17]
	v_exp_f32_e32 v110, v110
	v_exp_f32_e32 v111, v111
	v_exp_f32_e32 v112, v112
	v_exp_f32_e32 v113, v113
	ds_read_b128 v[158:161], v202 offset:22528
	ds_read_b128 v[154:157], v202 offset:23040
	s_waitcnt lgkmcnt(14)
	v_mfma_f32_32x32x16_bf16 v[18:33], v[122:125], v[74:77], v[18:33]
	v_exp_f32_e32 v82, v82
	v_exp_f32_e32 v83, v83
	v_exp_f32_e32 v84, v84
	v_exp_f32_e32 v85, v85
	s_waitcnt lgkmcnt(12)
	v_mfma_f32_32x32x16_bf16 v[2:17], v[122:125], v[50:53], v[2:17]
	v_exp_f32_e32 v86, v86
	v_exp_f32_e32 v87, v87
	v_exp_f32_e32 v88, v88
	v_exp_f32_e32 v89, v89
	s_waitcnt lgkmcnt(10)
	v_mfma_f32_32x32x16_bf16 v[18:33], v[114:117], v[54:57], v[18:33]
	v_exp_f32_e32 v90, v90
	v_exp_f32_e32 v91, v91
	v_exp_f32_e32 v92, v92
	v_exp_f32_e32 v93, v93
	s_setprio 2
	s_waitcnt vmcnt(2) lgkmcnt(0)
	s_barrier
	s_waitcnt lgkmcnt(8)
	v_mfma_f32_32x32x16_bf16 v[2:17], v[114:117], v[58:61], v[2:17]
	v_exp_f32_e32 v94, v94
	v_exp_f32_e32 v95, v95
	v_exp_f32_e32 v96, v96
	v_exp_f32_e32 v97, v97
	s_setprio 0

.Lf3e_0_489:
	s_waitcnt lgkmcnt(14)
	v_mfma_f32_32x32x16_bf16 v[18:33], v[138:141], v[150:153], v[18:33]
	v_exp_f32_e32 v66, v66
	v_exp_f32_e32 v67, v67
	v_exp_f32_e32 v68, v68
	v_exp_f32_e32 v69, v69
	ds_read_b128 v[174:177], v202 offset:0
	ds_read_b128 v[170:173], v202 offset:512
	s_waitcnt lgkmcnt(14)
	v_mfma_f32_32x32x16_bf16 v[2:17], v[138:141], v[146:149], v[2:17]
	v_exp_f32_e32 v70, v70
	v_exp_f32_e32 v71, v71
	v_exp_f32_e32 v72, v72
	v_exp_f32_e32 v73, v73
	ds_read_b128 v[166:169], v202 offset:2048
	ds_read_b128 v[162:165], v202 offset:2560
	s_waitcnt lgkmcnt(14)
	v_mfma_f32_32x32x16_bf16 v[18:33], v[130:133], v[98:101], v[18:33]
	v_exp_f32_e32 v74, v74
	v_exp_f32_e32 v75, v75
	v_exp_f32_e32 v76, v76
	v_exp_f32_e32 v77, v77
	ds_read_b128 v[158:161], v202 offset:4096
	ds_read_b128 v[154:157], v202 offset:4608
	s_waitcnt lgkmcnt(14)
	v_mfma_f32_32x32x16_bf16 v[2:17], v[130:133], v[102:105], v[2:17]
	v_exp_f32_e32 v78, v78
	v_exp_f32_e32 v79, v79
	v_exp_f32_e32 v80, v80
	v_exp_f32_e32 v81, v81
	ds_read_b128 v[150:153], v202 offset:6144
	ds_read_b128 v[146:149], v202 offset:6656
	s_waitcnt lgkmcnt(14)
	v_mfma_f32_32x32x16_bf16 v[18:33], v[122:125], v[106:109], v[18:33]
	v_exp_f32_e32 v50, v50
	v_exp_f32_e32 v51, v51
	v_exp_f32_e32 v52, v52
	v_exp_f32_e32 v53, v53
	s_waitcnt lgkmcnt(12)
	v_mfma_f32_32x32x16_bf16 v[2:17], v[122:125], v[82:85], v[2:17]
	v_exp_f32_e32 v54, v54
	v_exp_f32_e32 v55, v55
	v_exp_f32_e32 v56, v56
	v_exp_f32_e32 v57, v57
	s_waitcnt lgkmcnt(10)
	v_mfma_f32_32x32x16_bf16 v[18:33], v[114:117], v[86:89], v[18:33]
	v_exp_f32_e32 v58, v58
	v_exp_f32_e32 v59, v59
	v_exp_f32_e32 v60, v60
	v_exp_f32_e32 v61, v61
	s_setprio 2
	s_waitcnt vmcnt(2) lgkmcnt(0)
	s_barrier
	s_waitcnt lgkmcnt(8)
	v_mfma_f32_32x32x16_bf16 v[2:17], v[114:117], v[90:93], v[2:17]
	v_exp_f32_e32 v62, v62
	v_exp_f32_e32 v63, v63
	v_exp_f32_e32 v64, v64
	v_exp_f32_e32 v65, v65
	s_setprio 0

.Lf3e_1_486:
	s_waitcnt lgkmcnt(14)
	v_mfma_f32_32x32x16_bf16 v[18:33], v[138:141], v[178:181], v[18:33]
	v_exp_f32_e32 v98, v98
	v_exp_f32_e32 v99, v99
	v_exp_f32_e32 v100, v100
	v_exp_f32_e32 v101, v101
	ds_read_b128 v[62:65], v202 offset:8192
	ds_read_b128 v[178:181], v202 offset:10240
	s_waitcnt lgkmcnt(14)
	v_mfma_f32_32x32x16_bf16 v[2:17], v[138:141], v[174:177], v[2:17]
	v_exp_f32_e32 v102, v102
	v_exp_f32_e32 v103, v103
	v_exp_f32_e32 v104, v104
	v_exp_f32_e32 v105, v105
	ds_read_b128 v[174:177], v202 offset:8704
	ds_read_b128 v[170:173], v202 offset:10752
	s_waitcnt lgkmcnt(14)
	v_mfma_f32_32x32x16_bf16 v[18:33], v[130:133], v[66:69], v[18:33]
	v_exp_f32_e32 v106, v106
	v_exp_f32_e32 v107, v107
	v_exp_f32_e32 v108, v108
	v_exp_f32_e32 v109, v109
	ds_read_b128 v[166:169], v202 offset:12288
	ds_read_b128 v[162:165], v202 offset:12800
	s_waitcnt lgkmcnt(14)
	v_mfma_f32_32x32x16_bf16 v[2:17], v[130:133], v[70:73], v[2:17]
	v_exp_f32_e32 v110, v110
	v_exp_f32_e32 v111, v111
	v_exp_f32_e32 v112, v112
	v_exp_f32_e32 v113, v113
	ds_read_b128 v[158:161], v202 offset:14336
	ds_read_b128 v[154:157], v202 offset:14848
	s_waitcnt lgkmcnt(14)
	v_mfma_f32_32x32x16_bf16 v[18:33], v[122:125], v[74:77], v[18:33]
	v_exp_f32_e32 v82, v82
	v_exp_f32_e32 v83, v83
	v_exp_f32_e32 v84, v84
	v_exp_f32_e32 v85, v85
	s_waitcnt lgkmcnt(12)
	v_mfma_f32_32x32x16_bf16 v[2:17], v[122:125], v[50:53], v[2:17]
	v_exp_f32_e32 v86, v86
	v_exp_f32_e32 v87, v87
	v_exp_f32_e32 v88, v88
	v_exp_f32_e32 v89, v89
	s_waitcnt lgkmcnt(10)
	v_mfma_f32_32x32x16_bf16 v[18:33], v[114:117], v[54:57], v[18:33]
	v_exp_f32_e32 v90, v90
	v_exp_f32_e32 v91, v91
	v_exp_f32_e32 v92, v92
	v_exp_f32_e32 v93, v93
	s_setprio 2
	s_waitcnt vmcnt(2) lgkmcnt(0)
	s_barrier
	s_waitcnt lgkmcnt(8)
	v_mfma_f32_32x32x16_bf16 v[2:17], v[114:117], v[58:61], v[2:17]
	v_exp_f32_e32 v94, v94
	v_exp_f32_e32 v95, v95
	v_exp_f32_e32 v96, v96
	v_exp_f32_e32 v97, v97
	s_setprio 0

.Lf3e_1_489:
	s_waitcnt lgkmcnt(14)
	v_mfma_f32_32x32x16_bf16 v[18:33], v[138:141], v[150:153], v[18:33]
	v_exp_f32_e32 v66, v66
	v_exp_f32_e32 v67, v67
	v_exp_f32_e32 v68, v68
	v_exp_f32_e32 v69, v69
	ds_read_b128 v[174:177], v202 offset:16384
	ds_read_b128 v[170:173], v202 offset:16896
	s_waitcnt lgkmcnt(14)
	v_mfma_f32_32x32x16_bf16 v[2:17], v[138:141], v[146:149], v[2:17]
	v_exp_f32_e32 v70, v70
	v_exp_f32_e32 v71, v71
	v_exp_f32_e32 v72, v72
	v_exp_f32_e32 v73, v73
	ds_read_b128 v[166:169], v202 offset:18432
	ds_read_b128 v[162:165], v202 offset:18944
	s_waitcnt lgkmcnt(14)
	v_mfma_f32_32x32x16_bf16 v[18:33], v[130:133], v[98:101], v[18:33]
	v_exp_f32_e32 v74, v74
	v_exp_f32_e32 v75, v75
	v_exp_f32_e32 v76, v76
	v_exp_f32_e32 v77, v77
	ds_read_b128 v[158:161], v202 offset:20480
	ds_read_b128 v[154:157], v202 offset:20992
	s_waitcnt lgkmcnt(14)
	v_mfma_f32_32x32x16_bf16 v[2:17], v[130:133], v[102:105], v[2:17]
	v_exp_f32_e32 v78, v78
	v_exp_f32_e32 v79, v79
	v_exp_f32_e32 v80, v80
	v_exp_f32_e32 v81, v81
	ds_read_b128 v[150:153], v202 offset:22528
	ds_read_b128 v[146:149], v202 offset:23040
	s_waitcnt lgkmcnt(14)
	v_mfma_f32_32x32x16_bf16 v[18:33], v[122:125], v[106:109], v[18:33]
	v_exp_f32_e32 v50, v50
	v_exp_f32_e32 v51, v51
	v_exp_f32_e32 v52, v52
	v_exp_f32_e32 v53, v53
	s_waitcnt lgkmcnt(12)
	v_mfma_f32_32x32x16_bf16 v[2:17], v[122:125], v[82:85], v[2:17]
	v_exp_f32_e32 v54, v54
	v_exp_f32_e32 v55, v55
	v_exp_f32_e32 v56, v56
	v_exp_f32_e32 v57, v57
	s_waitcnt lgkmcnt(10)
	v_mfma_f32_32x32x16_bf16 v[18:33], v[114:117], v[86:89], v[18:33]
	v_exp_f32_e32 v58, v58
	v_exp_f32_e32 v59, v59
	v_exp_f32_e32 v60, v60
	v_exp_f32_e32 v61, v61
	s_setprio 2
	s_waitcnt vmcnt(2) lgkmcnt(0)
	s_barrier
	s_waitcnt lgkmcnt(8)
	v_mfma_f32_32x32x16_bf16 v[2:17], v[114:117], v[90:93], v[2:17]
	v_exp_f32_e32 v62, v62
	v_exp_f32_e32 v63, v63
	v_exp_f32_e32 v64, v64
	v_exp_f32_e32 v65, v65
	s_setprio 0

.Lf3e_2_486:
	s_waitcnt lgkmcnt(14)
	v_mfma_f32_32x32x16_bf16 v[18:33], v[138:141], v[178:181], v[18:33]
	v_exp_f32_e32 v98, v98
	v_exp_f32_e32 v99, v99
	v_exp_f32_e32 v100, v100
	v_exp_f32_e32 v101, v101
	ds_read_b128 v[62:65], v202 offset:0
	ds_read_b128 v[178:181], v202 offset:2048
	s_waitcnt lgkmcnt(14)
	v_mfma_f32_32x32x16_bf16 v[2:17], v[138:141], v[174:177], v[2:17]
	v_exp_f32_e32 v102, v102
	v_exp_f32_e32 v103, v103
	v_exp_f32_e32 v104, v104
	v_exp_f32_e32 v105, v105
	ds_read_b128 v[174:177], v202 offset:512
	ds_read_b128 v[170:173], v202 offset:2560
	s_waitcnt lgkmcnt(14)
	v_mfma_f32_32x32x16_bf16 v[18:33], v[130:133], v[66:69], v[18:33]
	v_exp_f32_e32 v106, v106
	v_exp_f32_e32 v107, v107
	v_exp_f32_e32 v108, v108
	v_exp_f32_e32 v109, v109
	ds_read_b128 v[166:169], v202 offset:4096
	ds_read_b128 v[162:165], v202 offset:4608
	s_waitcnt lgkmcnt(14)
	v_mfma_f32_32x32x16_bf16 v[2:17], v[130:133], v[70:73], v[2:17]
	v_exp_f32_e32 v110, v110
	v_exp_f32_e32 v111, v111
	v_exp_f32_e32 v112, v112
	v_exp_f32_e32 v113, v113
	ds_read_b128 v[158:161], v202 offset:6144
	ds_read_b128 v[154:157], v202 offset:6656
	s_waitcnt lgkmcnt(14)
	v_mfma_f32_32x32x16_bf16 v[18:33], v[122:125], v[74:77], v[18:33]
	v_exp_f32_e32 v82, v82
	v_exp_f32_e32 v83, v83
	v_exp_f32_e32 v84, v84
	v_exp_f32_e32 v85, v85
	s_waitcnt lgkmcnt(12)
	v_mfma_f32_32x32x16_bf16 v[2:17], v[122:125], v[50:53], v[2:17]
	v_exp_f32_e32 v86, v86
	v_exp_f32_e32 v87, v87
	v_exp_f32_e32 v88, v88
	v_exp_f32_e32 v89, v89
	s_waitcnt lgkmcnt(10)
	v_mfma_f32_32x32x16_bf16 v[18:33], v[114:117], v[54:57], v[18:33]
	v_exp_f32_e32 v90, v90
	v_exp_f32_e32 v91, v91
	v_exp_f32_e32 v92, v92
	v_exp_f32_e32 v93, v93
	s_setprio 2
	s_waitcnt vmcnt(2) lgkmcnt(0)
	s_barrier
	s_waitcnt lgkmcnt(8)
	v_mfma_f32_32x32x16_bf16 v[2:17], v[114:117], v[58:61], v[2:17]
	v_exp_f32_e32 v94, v94
	v_exp_f32_e32 v95, v95
	v_exp_f32_e32 v96, v96
	v_exp_f32_e32 v97, v97
	s_setprio 0

.Lf3e_2_489:
	s_waitcnt lgkmcnt(14)
	v_mfma_f32_32x32x16_bf16 v[18:33], v[138:141], v[150:153], v[18:33]
	v_exp_f32_e32 v66, v66
	v_exp_f32_e32 v67, v67
	v_exp_f32_e32 v68, v68
	v_exp_f32_e32 v69, v69
	ds_read_b128 v[174:177], v202 offset:8192
	ds_read_b128 v[170:173], v202 offset:8704
	s_waitcnt lgkmcnt(14)
	v_mfma_f32_32x32x16_bf16 v[2:17], v[138:141], v[146:149], v[2:17]
	v_exp_f32_e32 v70, v70
	v_exp_f32_e32 v71, v71
	v_exp_f32_e32 v72, v72
	v_exp_f32_e32 v73, v73
	ds_read_b128 v[166:169], v202 offset:10240
	ds_read_b128 v[162:165], v202 offset:10752
	s_waitcnt lgkmcnt(14)
	v_mfma_f32_32x32x16_bf16 v[18:33], v[130:133], v[98:101], v[18:33]
	v_exp_f32_e32 v74, v74
	v_exp_f32_e32 v75, v75
	v_exp_f32_e32 v76, v76
	v_exp_f32_e32 v77, v77
	ds_read_b128 v[158:161], v202 offset:12288
	ds_read_b128 v[154:157], v202 offset:12800
	s_waitcnt lgkmcnt(14)
	v_mfma_f32_32x32x16_bf16 v[2:17], v[130:133], v[102:105], v[2:17]
	v_exp_f32_e32 v78, v78
	v_exp_f32_e32 v79, v79
	v_exp_f32_e32 v80, v80
	v_exp_f32_e32 v81, v81
	ds_read_b128 v[150:153], v202 offset:14336
	ds_read_b128 v[146:149], v202 offset:14848
	s_waitcnt lgkmcnt(14)
	v_mfma_f32_32x32x16_bf16 v[18:33], v[122:125], v[106:109], v[18:33]
	v_exp_f32_e32 v50, v50
	v_exp_f32_e32 v51, v51
	v_exp_f32_e32 v52, v52
	v_exp_f32_e32 v53, v53
	s_waitcnt lgkmcnt(12)
	v_mfma_f32_32x32x16_bf16 v[2:17], v[122:125], v[82:85], v[2:17]
	v_exp_f32_e32 v54, v54
	v_exp_f32_e32 v55, v55
	v_exp_f32_e32 v56, v56
	v_exp_f32_e32 v57, v57
	s_waitcnt lgkmcnt(10)
	v_mfma_f32_32x32x16_bf16 v[18:33], v[114:117], v[86:89], v[18:33]
	v_exp_f32_e32 v58, v58
	v_exp_f32_e32 v59, v59
	v_exp_f32_e32 v60, v60
	v_exp_f32_e32 v61, v61
	s_setprio 2
	s_waitcnt vmcnt(2) lgkmcnt(0)
	s_barrier
	s_waitcnt lgkmcnt(8)
	v_mfma_f32_32x32x16_bf16 v[2:17], v[114:117], v[90:93], v[2:17]
	v_exp_f32_e32 v62, v62
	v_exp_f32_e32 v63, v63
	v_exp_f32_e32 v64, v64
	v_exp_f32_e32 v65, v65
	s_setprio 0

.Lfast3e_exit:
	s_add_i32 s10, s10, 4
	s_movk_i32 s11, 0x4000
	s_mov_b32 s14, 0
	s_movk_i32 s50, 0x2000
	s_movk_i32 s25, 0x4000
	s_branch .LBB0_500
.Lfast3l_head:
.Lf3l_0_485:
	ds_read_b64_tr_b16 v[178:179], v203 offset:24576
	ds_read_b64_tr_b16 v[180:181], v203 offset:25088
	s_waitcnt lgkmcnt(9)
	v_mfma_f32_32x32x16_bf16 v[98:113], v[174:177], v[142:145], v[34:49]
	v_add_f32_e32 v82, v66, v67
	v_add_f32_e32 v82, v68, v82
	v_add_f32_e32 v82, v69, v82
	v_add_f32_e32 v82, v70, v82
	v_add_f32_e32 v82, v71, v82
	v_cvt_pk_bf16_f32 v138, v66, v67
	v_cvt_pk_bf16_f32 v139, v68, v69
	ds_read_b64_tr_b16 v[174:175], v203 offset:28672
	ds_read_b64_tr_b16 v[176:177], v203 offset:29184
	v_add_f32_e32 v66, v72, v82
	s_waitcnt lgkmcnt(10)
	v_mfma_f32_32x32x16_bf16 v[82:97], v[170:173], v[142:145], v[34:49]
	v_add_f32_e32 v66, v73, v66
	v_add_f32_e32 v66, v74, v66
	v_add_f32_e32 v114, v75, v66
	v_cvt_pk_bf16_f32 v140, v70, v71
	v_cvt_pk_bf16_f32 v141, v72, v73
	ds_read_b64_tr_b16 v[66:67], v203 offset:25600
	ds_read_b64_tr_b16 v[68:69], v203 offset:26112
	s_waitcnt lgkmcnt(11)
	v_mfma_f32_32x32x16_bf16 v[98:113], v[166:169], v[134:137], v[98:113]
	v_add_f32_e32 v70, v76, v114
	v_add_f32_e32 v70, v77, v70
	v_add_f32_e32 v70, v78, v70
	v_add_f32_e32 v114, v79, v70
	v_cvt_pk_bf16_f32 v130, v74, v75
	v_cvt_pk_bf16_f32 v131, v76, v77
	ds_read_b64_tr_b16 v[70:71], v203 offset:29696
	ds_read_b64_tr_b16 v[72:73], v203 offset:30208
	s_waitcnt lgkmcnt(12)
	v_mfma_f32_32x32x16_bf16 v[82:97], v[162:165], v[134:137], v[82:97]
	v_add_f32_e32 v74, v80, v114
	v_add_f32_e32 v74, v81, v74
	v_add_f32_e32 v74, v50, v74
	v_add_f32_e32 v114, v51, v74
	v_cvt_pk_bf16_f32 v132, v78, v79
	v_cvt_pk_bf16_f32 v133, v80, v81
	ds_read_b64_tr_b16 v[74:75], v203 offset:26624
	ds_read_b64_tr_b16 v[76:77], v203 offset:27136
	s_waitcnt lgkmcnt(13)
	v_mfma_f32_32x32x16_bf16 v[98:113], v[158:161], v[126:129], v[98:113]
	v_add_f32_e32 v78, v52, v114
	v_add_f32_e32 v78, v53, v78
	v_add_f32_e32 v78, v54, v78
	v_add_f32_e32 v78, v55, v78
	v_cvt_pk_bf16_f32 v122, v50, v51
	v_cvt_pk_bf16_f32 v123, v52, v53
	ds_read_b64_tr_b16 v[50:51], v203 offset:30720
	ds_read_b64_tr_b16 v[52:53], v203 offset:31232
	s_waitcnt lgkmcnt(14)
	v_mfma_f32_32x32x16_bf16 v[82:97], v[154:157], v[126:129], v[82:97]
	v_add_f32_e32 v78, v56, v78
	v_add_f32_e32 v78, v57, v78
	v_add_f32_e32 v78, v58, v78
	v_add_f32_e32 v78, v59, v78
	v_cvt_pk_bf16_f32 v124, v54, v55
	v_cvt_pk_bf16_f32 v125, v56, v57
	ds_read_b64_tr_b16 v[54:55], v203 offset:27648
	ds_read_b64_tr_b16 v[56:57], v203 offset:28160
	s_waitcnt lgkmcnt(14)
	v_mfma_f32_32x32x16_bf16 v[98:113], v[150:153], v[118:121], v[98:113]
	v_add_f32_e32 v78, v60, v78
	v_add_f32_e32 v78, v61, v78
	v_add_f32_e32 v78, v62, v78
	v_add_f32_e32 v78, v63, v78
	v_cvt_pk_bf16_f32 v114, v58, v59
	v_cvt_pk_bf16_f32 v115, v60, v61
	ds_read_b64_tr_b16 v[58:59], v203 offset:31744
	ds_read_b64_tr_b16 v[60:61], v203 offset:32256
	v_mfma_f32_32x32x16_bf16 v[82:97], v[146:149], v[118:121], v[82:97]
	v_add_f32_e32 v78, v64, v78
	v_add_f32_e32 v78, v65, v78
	v_cvt_pk_bf16_f32 v116, v62, v63
	v_cvt_pk_bf16_f32 v117, v64, v65
	s_add_i32 s98, s46, 0x2000
	s_mov_b32 s5, m0
	s_mov_b32 m0, s98
	s_nop 0
	global_load_lds_dwordx4 v188, s[100:101]
	s_mov_b32 m0, s5
	s_add_i32 s98, s47, 0x4000
	s_mov_b32 s5, m0
	s_mov_b32 m0, s98
	s_nop 0
	global_load_lds_dwordx4 v186, s[100:101]
	s_mov_b32 m0, s5
	v_add_f32_e32 v190, v205, v78
.Lf3l_0_486:
	s_waitcnt lgkmcnt(14)
	v_mfma_f32_32x32x16_bf16 v[18:33], v[138:141], v[178:181], v[18:33]
	v_exp_f32_e32 v98, v98
	v_exp_f32_e32 v99, v99
	v_exp_f32_e32 v100, v100
	v_exp_f32_e32 v101, v101
	ds_read_b128 v[62:65], v202 offset:16384
	ds_read_b128 v[178:181], v202 offset:18432
	s_waitcnt lgkmcnt(14)
	v_mfma_f32_32x32x16_bf16 v[2:17], v[138:141], v[174:177], v[2:17]
	v_exp_f32_e32 v102, v102
	v_exp_f32_e32 v103, v103
	v_exp_f32_e32 v104, v104
	v_exp_f32_e32 v105, v105
	ds_read_b128 v[174:177], v202 offset:16896
	ds_read_b128 v[170:173], v202 offset:18944
	s_waitcnt lgkmcnt(14)
	v_mfma_f32_32x32x16_bf16 v[18:33], v[130:133], v[66:69], v[18:33]
	v_exp_f32_e32 v106, v106
	v_exp_f32_e32 v107, v107
	v_exp_f32_e32 v108, v108
	v_exp_f32_e32 v109, v109
	ds_read_b128 v[166:169], v202 offset:20480
	ds_read_b128 v[162:165], v202 offset:20992
	s_waitcnt lgkmcnt(14)
	v_mfma_f32_32x32x16_bf16 v[2:17], v[130:133], v[70:73], v[2:17]
	v_exp_f32_e32 v110, v110
	v_exp_f32_e32 v111, v111
	v_exp_f32_e32 v112, v112
	v_exp_f32_e32 v113, v113
	ds_read_b128 v[158:161], v202 offset:22528
	ds_read_b128 v[154:157], v202 offset:23040
	s_waitcnt lgkmcnt(14)
	v_mfma_f32_32x32x16_bf16 v[18:33], v[122:125], v[74:77], v[18:33]
	v_exp_f32_e32 v82, v82
	v_exp_f32_e32 v83, v83
	v_exp_f32_e32 v84, v84
	v_exp_f32_e32 v85, v85
	s_waitcnt lgkmcnt(12)
	v_mfma_f32_32x32x16_bf16 v[2:17], v[122:125], v[50:53], v[2:17]
	v_exp_f32_e32 v86, v86
	v_exp_f32_e32 v87, v87
	v_exp_f32_e32 v88, v88
	v_exp_f32_e32 v89, v89
	s_waitcnt lgkmcnt(10)
	v_mfma_f32_32x32x16_bf16 v[18:33], v[114:117], v[54:57], v[18:33]
	v_exp_f32_e32 v90, v90
	v_exp_f32_e32 v91, v91
	v_exp_f32_e32 v92, v92
	v_exp_f32_e32 v93, v93
	s_setprio 3
	s_waitcnt vmcnt(2) lgkmcnt(0)
	s_barrier
	s_waitcnt lgkmcnt(8)
	v_mfma_f32_32x32x16_bf16 v[2:17], v[114:117], v[58:61], v[2:17]
	v_exp_f32_e32 v94, v94
	v_exp_f32_e32 v95, v95
	v_exp_f32_e32 v96, v96
	v_exp_f32_e32 v97, v97
	s_setprio 1

.Lf3l_0_489:
	s_waitcnt lgkmcnt(14)
	v_mfma_f32_32x32x16_bf16 v[18:33], v[138:141], v[150:153], v[18:33]
	v_exp_f32_e32 v66, v66
	v_exp_f32_e32 v67, v67
	v_exp_f32_e32 v68, v68
	v_exp_f32_e32 v69, v69
	ds_read_b128 v[174:177], v202 offset:0
	ds_read_b128 v[170:173], v202 offset:512
	s_waitcnt lgkmcnt(14)
	v_mfma_f32_32x32x16_bf16 v[2:17], v[138:141], v[146:149], v[2:17]
	v_exp_f32_e32 v70, v70
	v_exp_f32_e32 v71, v71
	v_exp_f32_e32 v72, v72
	v_exp_f32_e32 v73, v73
	ds_read_b128 v[166:169], v202 offset:2048
	ds_read_b128 v[162:165], v202 offset:2560
	s_waitcnt lgkmcnt(14)
	v_mfma_f32_32x32x16_bf16 v[18:33], v[130:133], v[98:101], v[18:33]
	v_exp_f32_e32 v74, v74
	v_exp_f32_e32 v75, v75
	v_exp_f32_e32 v76, v76
	v_exp_f32_e32 v77, v77
	ds_read_b128 v[158:161], v202 offset:4096
	ds_read_b128 v[154:157], v202 offset:4608
	s_waitcnt lgkmcnt(14)
	v_mfma_f32_32x32x16_bf16 v[2:17], v[130:133], v[102:105], v[2:17]
	v_exp_f32_e32 v78, v78
	v_exp_f32_e32 v79, v79
	v_exp_f32_e32 v80, v80
	v_exp_f32_e32 v81, v81
	ds_read_b128 v[150:153], v202 offset:6144
	ds_read_b128 v[146:149], v202 offset:6656
	s_waitcnt lgkmcnt(14)
	v_mfma_f32_32x32x16_bf16 v[18:33], v[122:125], v[106:109], v[18:33]
	v_exp_f32_e32 v50, v50
	v_exp_f32_e32 v51, v51
	v_exp_f32_e32 v52, v52
	v_exp_f32_e32 v53, v53
	s_waitcnt lgkmcnt(12)
	v_mfma_f32_32x32x16_bf16 v[2:17], v[122:125], v[82:85], v[2:17]
	v_exp_f32_e32 v54, v54
	v_exp_f32_e32 v55, v55
	v_exp_f32_e32 v56, v56
	v_exp_f32_e32 v57, v57
	s_waitcnt lgkmcnt(10)
	v_mfma_f32_32x32x16_bf16 v[18:33], v[114:117], v[86:89], v[18:33]
	v_exp_f32_e32 v58, v58
	v_exp_f32_e32 v59, v59
	v_exp_f32_e32 v60, v60
	v_exp_f32_e32 v61, v61
	s_setprio 3
	s_waitcnt vmcnt(2) lgkmcnt(0)
	s_barrier
	s_waitcnt lgkmcnt(8)
	v_mfma_f32_32x32x16_bf16 v[2:17], v[114:117], v[90:93], v[2:17]
	v_exp_f32_e32 v62, v62
	v_exp_f32_e32 v63, v63
	v_exp_f32_e32 v64, v64
	v_exp_f32_e32 v65, v65
	s_setprio 1

.Lf3l_1_486:
	s_waitcnt lgkmcnt(14)
	v_mfma_f32_32x32x16_bf16 v[18:33], v[138:141], v[178:181], v[18:33]
	v_exp_f32_e32 v98, v98
	v_exp_f32_e32 v99, v99
	v_exp_f32_e32 v100, v100
	v_exp_f32_e32 v101, v101
	ds_read_b128 v[62:65], v202 offset:8192
	ds_read_b128 v[178:181], v202 offset:10240
	s_waitcnt lgkmcnt(14)
	v_mfma_f32_32x32x16_bf16 v[2:17], v[138:141], v[174:177], v[2:17]
	v_exp_f32_e32 v102, v102
	v_exp_f32_e32 v103, v103
	v_exp_f32_e32 v104, v104
	v_exp_f32_e32 v105, v105
	ds_read_b128 v[174:177], v202 offset:8704
	ds_read_b128 v[170:173], v202 offset:10752
	s_waitcnt lgkmcnt(14)
	v_mfma_f32_32x32x16_bf16 v[18:33], v[130:133], v[66:69], v[18:33]
	v_exp_f32_e32 v106, v106
	v_exp_f32_e32 v107, v107
	v_exp_f32_e32 v108, v108
	v_exp_f32_e32 v109, v109
	ds_read_b128 v[166:169], v202 offset:12288
	ds_read_b128 v[162:165], v202 offset:12800
	s_waitcnt lgkmcnt(14)
	v_mfma_f32_32x32x16_bf16 v[2:17], v[130:133], v[70:73], v[2:17]
	v_exp_f32_e32 v110, v110
	v_exp_f32_e32 v111, v111
	v_exp_f32_e32 v112, v112
	v_exp_f32_e32 v113, v113
	ds_read_b128 v[158:161], v202 offset:14336
	ds_read_b128 v[154:157], v202 offset:14848
	s_waitcnt lgkmcnt(14)
	v_mfma_f32_32x32x16_bf16 v[18:33], v[122:125], v[74:77], v[18:33]
	v_exp_f32_e32 v82, v82
	v_exp_f32_e32 v83, v83
	v_exp_f32_e32 v84, v84
	v_exp_f32_e32 v85, v85
	s_waitcnt lgkmcnt(12)
	v_mfma_f32_32x32x16_bf16 v[2:17], v[122:125], v[50:53], v[2:17]
	v_exp_f32_e32 v86, v86
	v_exp_f32_e32 v87, v87
	v_exp_f32_e32 v88, v88
	v_exp_f32_e32 v89, v89
	s_waitcnt lgkmcnt(10)
	v_mfma_f32_32x32x16_bf16 v[18:33], v[114:117], v[54:57], v[18:33]
	v_exp_f32_e32 v90, v90
	v_exp_f32_e32 v91, v91
	v_exp_f32_e32 v92, v92
	v_exp_f32_e32 v93, v93
	s_setprio 3
	s_waitcnt vmcnt(2) lgkmcnt(0)
	s_barrier
	s_waitcnt lgkmcnt(8)
	v_mfma_f32_32x32x16_bf16 v[2:17], v[114:117], v[58:61], v[2:17]
	v_exp_f32_e32 v94, v94
	v_exp_f32_e32 v95, v95
	v_exp_f32_e32 v96, v96
	v_exp_f32_e32 v97, v97
	s_setprio 1

.Lf3l_1_489:
	s_waitcnt lgkmcnt(14)
	v_mfma_f32_32x32x16_bf16 v[18:33], v[138:141], v[150:153], v[18:33]
	v_exp_f32_e32 v66, v66
	v_exp_f32_e32 v67, v67
	v_exp_f32_e32 v68, v68
	v_exp_f32_e32 v69, v69
	ds_read_b128 v[174:177], v202 offset:16384
	ds_read_b128 v[170:173], v202 offset:16896
	s_waitcnt lgkmcnt(14)
	v_mfma_f32_32x32x16_bf16 v[2:17], v[138:141], v[146:149], v[2:17]
	v_exp_f32_e32 v70, v70
	v_exp_f32_e32 v71, v71
	v_exp_f32_e32 v72, v72
	v_exp_f32_e32 v73, v73
	ds_read_b128 v[166:169], v202 offset:18432
	ds_read_b128 v[162:165], v202 offset:18944
	s_waitcnt lgkmcnt(14)
	v_mfma_f32_32x32x16_bf16 v[18:33], v[130:133], v[98:101], v[18:33]
	v_exp_f32_e32 v74, v74
	v_exp_f32_e32 v75, v75
	v_exp_f32_e32 v76, v76
	v_exp_f32_e32 v77, v77
	ds_read_b128 v[158:161], v202 offset:20480
	ds_read_b128 v[154:157], v202 offset:20992
	s_waitcnt lgkmcnt(14)
	v_mfma_f32_32x32x16_bf16 v[2:17], v[130:133], v[102:105], v[2:17]
	v_exp_f32_e32 v78, v78
	v_exp_f32_e32 v79, v79
	v_exp_f32_e32 v80, v80
	v_exp_f32_e32 v81, v81
	ds_read_b128 v[150:153], v202 offset:22528
	ds_read_b128 v[146:149], v202 offset:23040
	s_waitcnt lgkmcnt(14)
	v_mfma_f32_32x32x16_bf16 v[18:33], v[122:125], v[106:109], v[18:33]
	v_exp_f32_e32 v50, v50
	v_exp_f32_e32 v51, v51
	v_exp_f32_e32 v52, v52
	v_exp_f32_e32 v53, v53
	s_waitcnt lgkmcnt(12)
	v_mfma_f32_32x32x16_bf16 v[2:17], v[122:125], v[82:85], v[2:17]
	v_exp_f32_e32 v54, v54
	v_exp_f32_e32 v55, v55
	v_exp_f32_e32 v56, v56
	v_exp_f32_e32 v57, v57
	s_waitcnt lgkmcnt(10)
	v_mfma_f32_32x32x16_bf16 v[18:33], v[114:117], v[86:89], v[18:33]
	v_exp_f32_e32 v58, v58
	v_exp_f32_e32 v59, v59
	v_exp_f32_e32 v60, v60
	v_exp_f32_e32 v61, v61
	s_setprio 3
	s_waitcnt vmcnt(2) lgkmcnt(0)
	s_barrier
	s_waitcnt lgkmcnt(8)
	v_mfma_f32_32x32x16_bf16 v[2:17], v[114:117], v[90:93], v[2:17]
	v_exp_f32_e32 v62, v62
	v_exp_f32_e32 v63, v63
	v_exp_f32_e32 v64, v64
	v_exp_f32_e32 v65, v65
	s_setprio 1

.Lf3l_2_486:
	s_waitcnt lgkmcnt(14)
	v_mfma_f32_32x32x16_bf16 v[18:33], v[138:141], v[178:181], v[18:33]
	v_exp_f32_e32 v98, v98
	v_exp_f32_e32 v99, v99
	v_exp_f32_e32 v100, v100
	v_exp_f32_e32 v101, v101
	ds_read_b128 v[62:65], v202 offset:0
	ds_read_b128 v[178:181], v202 offset:2048
	s_waitcnt lgkmcnt(14)
	v_mfma_f32_32x32x16_bf16 v[2:17], v[138:141], v[174:177], v[2:17]
	v_exp_f32_e32 v102, v102
	v_exp_f32_e32 v103, v103
	v_exp_f32_e32 v104, v104
	v_exp_f32_e32 v105, v105
	ds_read_b128 v[174:177], v202 offset:512
	ds_read_b128 v[170:173], v202 offset:2560
	s_waitcnt lgkmcnt(14)
	v_mfma_f32_32x32x16_bf16 v[18:33], v[130:133], v[66:69], v[18:33]
	v_exp_f32_e32 v106, v106
	v_exp_f32_e32 v107, v107
	v_exp_f32_e32 v108, v108
	v_exp_f32_e32 v109, v109
	ds_read_b128 v[166:169], v202 offset:4096
	ds_read_b128 v[162:165], v202 offset:4608
	s_waitcnt lgkmcnt(14)
	v_mfma_f32_32x32x16_bf16 v[2:17], v[130:133], v[70:73], v[2:17]
	v_exp_f32_e32 v110, v110
	v_exp_f32_e32 v111, v111
	v_exp_f32_e32 v112, v112
	v_exp_f32_e32 v113, v113
	ds_read_b128 v[158:161], v202 offset:6144
	ds_read_b128 v[154:157], v202 offset:6656
	s_waitcnt lgkmcnt(14)
	v_mfma_f32_32x32x16_bf16 v[18:33], v[122:125], v[74:77], v[18:33]
	v_exp_f32_e32 v82, v82
	v_exp_f32_e32 v83, v83
	v_exp_f32_e32 v84, v84
	v_exp_f32_e32 v85, v85
	s_waitcnt lgkmcnt(12)
	v_mfma_f32_32x32x16_bf16 v[2:17], v[122:125], v[50:53], v[2:17]
	v_exp_f32_e32 v86, v86
	v_exp_f32_e32 v87, v87
	v_exp_f32_e32 v88, v88
	v_exp_f32_e32 v89, v89
	s_waitcnt lgkmcnt(10)
	v_mfma_f32_32x32x16_bf16 v[18:33], v[114:117], v[54:57], v[18:33]
	v_exp_f32_e32 v90, v90
	v_exp_f32_e32 v91, v91
	v_exp_f32_e32 v92, v92
	v_exp_f32_e32 v93, v93
	s_setprio 3
	s_waitcnt vmcnt(2) lgkmcnt(0)
	s_barrier
	s_waitcnt lgkmcnt(8)
	v_mfma_f32_32x32x16_bf16 v[2:17], v[114:117], v[58:61], v[2:17]
	v_exp_f32_e32 v94, v94
	v_exp_f32_e32 v95, v95
	v_exp_f32_e32 v96, v96
	v_exp_f32_e32 v97, v97
	s_setprio 1

.Lf3l_2_489:
	s_waitcnt lgkmcnt(14)
	v_mfma_f32_32x32x16_bf16 v[18:33], v[138:141], v[150:153], v[18:33]
	v_exp_f32_e32 v66, v66
	v_exp_f32_e32 v67, v67
	v_exp_f32_e32 v68, v68
	v_exp_f32_e32 v69, v69
	ds_read_b128 v[174:177], v202 offset:8192
	ds_read_b128 v[170:173], v202 offset:8704
	s_waitcnt lgkmcnt(14)
	v_mfma_f32_32x32x16_bf16 v[2:17], v[138:141], v[146:149], v[2:17]
	v_exp_f32_e32 v70, v70
	v_exp_f32_e32 v71, v71
	v_exp_f32_e32 v72, v72
	v_exp_f32_e32 v73, v73
	ds_read_b128 v[166:169], v202 offset:10240
	ds_read_b128 v[162:165], v202 offset:10752
	s_waitcnt lgkmcnt(14)
	v_mfma_f32_32x32x16_bf16 v[18:33], v[130:133], v[98:101], v[18:33]
	v_exp_f32_e32 v74, v74
	v_exp_f32_e32 v75, v75
	v_exp_f32_e32 v76, v76
	v_exp_f32_e32 v77, v77
	ds_read_b128 v[158:161], v202 offset:12288
	ds_read_b128 v[154:157], v202 offset:12800
	s_waitcnt lgkmcnt(14)
	v_mfma_f32_32x32x16_bf16 v[2:17], v[130:133], v[102:105], v[2:17]
	v_exp_f32_e32 v78, v78
	v_exp_f32_e32 v79, v79
	v_exp_f32_e32 v80, v80
	v_exp_f32_e32 v81, v81
	ds_read_b128 v[150:153], v202 offset:14336
	ds_read_b128 v[146:149], v202 offset:14848
	s_waitcnt lgkmcnt(14)
	v_mfma_f32_32x32x16_bf16 v[18:33], v[122:125], v[106:109], v[18:33]
	v_exp_f32_e32 v50, v50
	v_exp_f32_e32 v51, v51
	v_exp_f32_e32 v52, v52
	v_exp_f32_e32 v53, v53
	s_waitcnt lgkmcnt(12)
	v_mfma_f32_32x32x16_bf16 v[2:17], v[122:125], v[82:85], v[2:17]
	v_exp_f32_e32 v54, v54
	v_exp_f32_e32 v55, v55
	v_exp_f32_e32 v56, v56
	v_exp_f32_e32 v57, v57
	s_waitcnt lgkmcnt(10)
	v_mfma_f32_32x32x16_bf16 v[18:33], v[114:117], v[86:89], v[18:33]
	v_exp_f32_e32 v58, v58
	v_exp_f32_e32 v59, v59
	v_exp_f32_e32 v60, v60
	v_exp_f32_e32 v61, v61
	s_setprio 3
	s_waitcnt vmcnt(2) lgkmcnt(0)
	s_barrier
	s_waitcnt lgkmcnt(8)
	v_mfma_f32_32x32x16_bf16 v[2:17], v[114:117], v[90:93], v[2:17]
	v_exp_f32_e32 v62, v62
	v_exp_f32_e32 v63, v63
	v_exp_f32_e32 v64, v64
	v_exp_f32_e32 v65, v65
	s_setprio 1
